# P1: counted vmcnt per epilogue path + peeled first K-iteration without the two redundant vmcnt waits; P0 w_in transposer loads batched; fixup prologue loads batched; P3 residual loads hoisted
# speedup vs baseline: 1.0063x; 1.0063x over previous
; #define LAS __attribute__((address_space(3)))
; #define LDSW() asm volatile("s_waitcnt lgkmcnt(0)" ::: "memory")
; __device__ __forceinline__ void tr_item(const float* src, size_t spitch, int nvalid, const float* scale, bf16_t* dst, size_t dpitch, LAS float* scr, int lane) {
;     const int n = lane & 31;
; #pragma unroll 16
;     for (int i = 0; i < 32; ++i) { const int kk = 2 * i + (lane >> 5); float v = (n < nvalid) ? src[(size_t)kk * spitch + n] : 0.f; if (scale) v *= scale[kk]; scr[kk * 33 + n] = v; }
;     LDSW();
.LBB0_16:
	s_add_u32 s34, s34, 0x80400
	s_addc_u32 s35, s35, 0
	v_add_u32_e32 v75, 0x1080, v75
	s_cmp_lg_u32 s34, 0x100800
	v_lshl_add_u64 v[94:95], v[94:95], 0, s[26:27]
	s_cbranch_scc0 .LBB0_10
.LBB0_17:
	v_lshl_add_u64 v[128:129], v[92:93], 0, s[34:35]
	s_mov_b32 s98, 0x8040
	s_mov_b32 s99, 0
	v_mov_b32_e32 v130, 0
	v_mov_b32_e32 v131, 0
	v_mov_b32_e32 v132, 0
	v_mov_b32_e32 v133, 0
	v_mov_b32_e32 v134, 0
	v_mov_b32_e32 v135, 0
	v_mov_b32_e32 v136, 0
	v_mov_b32_e32 v137, 0
	v_mov_b32_e32 v138, 0
	v_mov_b32_e32 v139, 0
	v_mov_b32_e32 v140, 0
	v_mov_b32_e32 v141, 0
	v_mov_b32_e32 v142, 0
	v_mov_b32_e32 v143, 0
	v_mov_b32_e32 v144, 0
	v_mov_b32_e32 v145, 0
	s_and_saveexec_b64 s[36:37], s[30:31]
	s_cbranch_execz .Ltr_noload
	global_load_dword v130, v[128:129], off
	v_lshl_add_u64 v[128:129], v[128:129], 0, s[98:99]
	global_load_dword v131, v[128:129], off
	v_lshl_add_u64 v[128:129], v[128:129], 0, s[98:99]
	global_load_dword v132, v[128:129], off
	v_lshl_add_u64 v[128:129], v[128:129], 0, s[98:99]
	global_load_dword v133, v[128:129], off
	v_lshl_add_u64 v[128:129], v[128:129], 0, s[98:99]
	global_load_dword v134, v[128:129], off
	v_lshl_add_u64 v[128:129], v[128:129], 0, s[98:99]
	global_load_dword v135, v[128:129], off
	v_lshl_add_u64 v[128:129], v[128:129], 0, s[98:99]
	global_load_dword v136, v[128:129], off
	v_lshl_add_u64 v[128:129], v[128:129], 0, s[98:99]
	global_load_dword v137, v[128:129], off
	v_lshl_add_u64 v[128:129], v[128:129], 0, s[98:99]
	global_load_dword v138, v[128:129], off
	v_lshl_add_u64 v[128:129], v[128:129], 0, s[98:99]
	global_load_dword v139, v[128:129], off
	v_lshl_add_u64 v[128:129], v[128:129], 0, s[98:99]
	global_load_dword v140, v[128:129], off
	v_lshl_add_u64 v[128:129], v[128:129], 0, s[98:99]
	global_load_dword v141, v[128:129], off
	v_lshl_add_u64 v[128:129], v[128:129], 0, s[98:99]
	global_load_dword v142, v[128:129], off
	v_lshl_add_u64 v[128:129], v[128:129], 0, s[98:99]
	global_load_dword v143, v[128:129], off
	v_lshl_add_u64 v[128:129], v[128:129], 0, s[98:99]
	global_load_dword v144, v[128:129], off
	v_lshl_add_u64 v[128:129], v[128:129], 0, s[98:99]
	global_load_dword v145, v[128:129], off
.Ltr_noload:
	s_or_b64 exec, exec, s[36:37]
	s_andn2_b64 vcc, exec, s[12:13]
	s_cbranch_vccnz .Ltr_noscale
	global_load_dword v146, v[94:95], off offset:-120
	global_load_dword v147, v[94:95], off offset:-112
	global_load_dword v148, v[94:95], off offset:-104
	global_load_dword v149, v[94:95], off offset:-96
	global_load_dword v150, v[94:95], off offset:-88
	global_load_dword v151, v[94:95], off offset:-80
	global_load_dword v152, v[94:95], off offset:-72
	global_load_dword v153, v[94:95], off offset:-64
	global_load_dword v154, v[94:95], off offset:-56
	global_load_dword v155, v[94:95], off offset:-48
	global_load_dword v156, v[94:95], off offset:-40
	global_load_dword v157, v[94:95], off offset:-32
	global_load_dword v158, v[94:95], off offset:-24
	global_load_dword v159, v[94:95], off offset:-16
	global_load_dword v160, v[94:95], off offset:-8
	global_load_dword v161, v[94:95], off
	s_waitcnt vmcnt(15)
	v_mul_f32_e32 v130, v130, v146
	s_waitcnt vmcnt(14)
	v_mul_f32_e32 v131, v131, v147
	s_waitcnt vmcnt(13)
	v_mul_f32_e32 v132, v132, v148
	s_waitcnt vmcnt(12)
	v_mul_f32_e32 v133, v133, v149
	s_waitcnt vmcnt(11)
	v_mul_f32_e32 v134, v134, v150
	s_waitcnt vmcnt(10)
	v_mul_f32_e32 v135, v135, v151
	s_waitcnt vmcnt(9)
	v_mul_f32_e32 v136, v136, v152
	s_waitcnt vmcnt(8)
	v_mul_f32_e32 v137, v137, v153
	s_waitcnt vmcnt(7)
	v_mul_f32_e32 v138, v138, v154
	s_waitcnt vmcnt(6)
	v_mul_f32_e32 v139, v139, v155
	s_waitcnt vmcnt(5)
	v_mul_f32_e32 v140, v140, v156
	s_waitcnt vmcnt(4)
	v_mul_f32_e32 v141, v141, v157
	s_waitcnt vmcnt(3)
	v_mul_f32_e32 v142, v142, v158
	s_waitcnt vmcnt(2)
	v_mul_f32_e32 v143, v143, v159
	s_waitcnt vmcnt(1)
	v_mul_f32_e32 v144, v144, v160
	s_waitcnt vmcnt(0)
	v_mul_f32_e32 v145, v145, v161
.Ltr_noscale:
	s_waitcnt vmcnt(0)
	ds_write_b32 v75, v130
	ds_write_b32 v75, v131 offset:264
	ds_write_b32 v75, v132 offset:528
	ds_write_b32 v75, v133 offset:792
	ds_write_b32 v75, v134 offset:1056
	ds_write_b32 v75, v135 offset:1320
	ds_write_b32 v75, v136 offset:1584
	ds_write_b32 v75, v137 offset:1848
	ds_write_b32 v75, v138 offset:2112
	ds_write_b32 v75, v139 offset:2376
	ds_write_b32 v75, v140 offset:2640
	ds_write_b32 v75, v141 offset:2904
	ds_write_b32 v75, v142 offset:3168
	ds_write_b32 v75, v143 offset:3432
	ds_write_b32 v75, v144 offset:3696
	ds_write_b32 v75, v145 offset:3960
	s_branch .LBB0_16

; #define PG8_STAGE(bufoff, gbase, voff) do { _Pragma("unroll") for (int _i = 0; _i < 2; ++_i) \
;         __builtin_amdgcn_global_load_lds((const unsigned*)((const char*)(gbase) + (voff)[_i]), (PG8_LAS unsigned*)(lds + (bufoff) + ldsw + _i * 8192), 16, 0, 0); } while (0)
; #define PG8_LDA(dst, b, h) do { _Pragma("unroll") for (int m = 0; m < 4; ++m) _Pragma("unroll") for (int k = 0; k < 2; ++k) dst[m][k] = *(const PG8_LAS bf16x8*)(lds + PG8_SA(b, h) + aoff + m * 2048 + k * 1024); } while (0)
; #define PG8_LDB(dst, b, h) do { _Pragma("unroll") for (int n = 0; n < 2; ++n) _Pragma("unroll") for (int k = 0; k < 2; ++k) dst[n][k] = *(const PG8_LAS bf16x8*)(lds + PG8_SB(b, h) + boff + n * 2048 + k * 1024); } while (0)
; #define PG8_MMA(ai, bj, At, Bt) do { __builtin_amdgcn_s_setprio(1); _Pragma("unroll") for (int m = 0; m < 4; ++m) _Pragma("unroll") for (int n = 0; n < 2; ++n) _Pragma("unroll") for (int k = 0; k < 2; ++k) \
;         acc[ai][bj][m][n] = __builtin_amdgcn_mfma_f32_16x16x32_bf16(Bt[n][k], At[m][k], acc[ai][bj][m][n], 0, 0, 0); __builtin_amdgcn_s_setprio(0); } while (0)
; #define PG8_WAIT_V(n) asm volatile("s_waitcnt vmcnt(" #n ")" ::: "memory")
; #define PG8_WAIT_L(n) asm volatile("s_waitcnt lgkmcnt(" #n ")" ::: "memory")
; #define PG8_BAR __builtin_amdgcn_s_barrier()
; #define PG8_SCHED __builtin_amdgcn_sched_barrier(0)
; template <class Epi, class Sched, bool ALIGN_EPI = false, bool SP2 = false>
; __device__ __forceinline__ void gemm_phase(PG8_LAS unsigned char* lds, const Gemm g, const Sched& S, const Epi& E) {
;     ...
;             PG8_LDB(B0, 0, 0); PG8_LDB(B1, 0, 1); PG8_SCHED; PG8_LDA(At, 0, 0); PG8_STAGE(PG8_SA(1, 1), a1 + hstep, voffA);
;             PG8_WAIT_V(8); PG8_WAIT_L(0); PG8_BAR; PG8_MMA(0, 0, At, B0); PG8_MMA(0, 1, At, B1); PG8_BAR; PG8_SCHED;
;     ...
;         for (int a = 0; a < 2; ++a)
; #pragma unroll
;             for (int b = 0; b < 2; ++b)
; #pragma unroll
;                 for (int m = 0; m < 4; ++m)
; #pragma unroll
;                     for (int n = 0; n < 2; ++n) acc[a][b][m][n] = (f32x4){0.f, 0.f, 0.f, 0.f};
.LBB0_156:
	s_ashr_i32 s49, s48, 31
	s_lshl_b64 s[34:35], s[48:49], 19
	s_add_u32 s50, s92, s34
	s_addc_u32 s51, s93, s35
	s_and_b64 s[34:35], s[42:43], exec
	s_cselect_b32 s5, s51, s23
	s_cselect_b32 s7, s50, s22
	s_ashr_i32 s47, s46, 31
	s_lshl_b64 s[34:35], s[46:47], 19
	s_add_u32 s52, s20, s34
	s_addc_u32 s53, s21, s35
	s_and_b64 s[34:35], s[42:43], exec
	s_cselect_b32 s34, s53, s41
	s_cselect_b32 s35, s52, s40
	s_add_u32 s22, s22, 0x40080
	s_addc_u32 s23, s23, 0
	s_add_u32 s45, s40, 0x100
	v_mov_b32_e32 v2, 0
	s_addc_u32 s47, s41, 0
	s_mov_b32 s49, -2
	s_waitcnt lgkmcnt(0)
	v_mov_b32_e32 v3, v2
	v_mov_b32_e32 v4, v2
	v_mov_b32_e32 v5, v2
	v_mov_b32_e32 v6, v2
	v_mov_b32_e32 v7, v2
	v_mov_b32_e32 v8, v2
	v_mov_b32_e32 v9, v2
	v_mov_b32_e32 v18, v2
	v_mov_b32_e32 v19, v2
	v_mov_b32_e32 v20, v2
	v_mov_b32_e32 v21, v2
	v_mov_b32_e32 v22, v2
	v_mov_b32_e32 v23, v2
	v_mov_b32_e32 v24, v2
	v_mov_b32_e32 v25, v2
	v_mov_b32_e32 v34, v2
	v_mov_b32_e32 v35, v2
	v_mov_b32_e32 v36, v2
	v_mov_b32_e32 v37, v2
	v_mov_b32_e32 v38, v2
	v_mov_b32_e32 v39, v2
	v_mov_b32_e32 v40, v2
	v_mov_b32_e32 v41, v2
	v_mov_b32_e32 v50, v2
	v_mov_b32_e32 v51, v2
	v_mov_b32_e32 v52, v2
	v_mov_b32_e32 v53, v2
	v_mov_b32_e32 v54, v2
	v_mov_b32_e32 v55, v2
	v_mov_b32_e32 v56, v2
	v_mov_b32_e32 v57, v2
	v_mov_b32_e32 v10, v2
	v_mov_b32_e32 v11, v2
	v_mov_b32_e32 v12, v2
	v_mov_b32_e32 v13, v2
	v_mov_b32_e32 v14, v2
	v_mov_b32_e32 v15, v2
	v_mov_b32_e32 v16, v2
	v_mov_b32_e32 v17, v2
	v_mov_b32_e32 v26, v2
	v_mov_b32_e32 v27, v2
	v_mov_b32_e32 v28, v2
	v_mov_b32_e32 v29, v2
	v_mov_b32_e32 v30, v2
	v_mov_b32_e32 v31, v2
	v_mov_b32_e32 v32, v2
	v_mov_b32_e32 v33, v2
	v_mov_b32_e32 v42, v2
	v_mov_b32_e32 v43, v2
	v_mov_b32_e32 v44, v2
	v_mov_b32_e32 v45, v2
	v_mov_b32_e32 v46, v2
	v_mov_b32_e32 v47, v2
	v_mov_b32_e32 v48, v2
	v_mov_b32_e32 v49, v2
	v_mov_b32_e32 v58, v2
	v_mov_b32_e32 v59, v2
	v_mov_b32_e32 v60, v2
	v_mov_b32_e32 v61, v2
	v_mov_b32_e32 v62, v2
	v_mov_b32_e32 v63, v2
	s_waitcnt vmcnt(0)
	v_mov_b32_e32 v64, v2
	v_mov_b32_e32 v65, v2
	v_mov_b32_e32 v66, v2
	v_mov_b32_e32 v67, v2
	v_mov_b32_e32 v68, v2
	v_mov_b32_e32 v69, v2
	v_mov_b32_e32 v70, v2
	v_mov_b32_e32 v71, v2
	v_mov_b32_e32 v72, v2
	v_mov_b32_e32 v73, v2
	v_mov_b32_e32 v114, v2
	v_mov_b32_e32 v115, v2
	v_mov_b32_e32 v116, v2
	v_mov_b32_e32 v117, v2
	v_mov_b32_e32 v118, v2
	v_mov_b32_e32 v119, v2
	v_mov_b32_e32 v120, v2
	v_mov_b32_e32 v121, v2
	v_mov_b32_e32 v130, v2
	v_mov_b32_e32 v131, v2
	v_mov_b32_e32 v132, v2
	v_mov_b32_e32 v133, v2
	v_mov_b32_e32 v134, v2
	v_mov_b32_e32 v135, v2
	v_mov_b32_e32 v136, v2
	v_mov_b32_e32 v137, v2
	v_mov_b32_e32 v146, v2
	v_mov_b32_e32 v147, v2
	v_mov_b32_e32 v148, v2
	v_mov_b32_e32 v149, v2
	v_mov_b32_e32 v150, v2
	v_mov_b32_e32 v151, v2
	v_mov_b32_e32 v152, v2
	v_mov_b32_e32 v153, v2
	v_mov_b32_e32 v86, v2
	v_mov_b32_e32 v87, v2
	v_mov_b32_e32 v88, v2
	v_mov_b32_e32 v89, v2
	v_mov_b32_e32 v106, v2
	v_mov_b32_e32 v107, v2
	v_mov_b32_e32 v108, v2
	v_mov_b32_e32 v109, v2
	v_mov_b32_e32 v122, v2
	v_mov_b32_e32 v123, v2
	v_mov_b32_e32 v124, v2
	v_mov_b32_e32 v125, v2
	v_mov_b32_e32 v126, v2
	v_mov_b32_e32 v127, v2
	v_mov_b32_e32 v128, v2
	v_mov_b32_e32 v129, v2
	v_mov_b32_e32 v138, v2
	v_mov_b32_e32 v139, v2
	v_mov_b32_e32 v140, v2
	v_mov_b32_e32 v141, v2
	v_mov_b32_e32 v142, v2
	v_mov_b32_e32 v143, v2
	v_mov_b32_e32 v144, v2
	v_mov_b32_e32 v145, v2
	v_mov_b32_e32 v154, v2
	v_mov_b32_e32 v155, v2
	v_mov_b32_e32 v156, v2
	v_mov_b32_e32 v157, v2
	v_mov_b32_e32 v158, v2
	v_mov_b32_e32 v159, v2
	v_mov_b32_e32 v160, v2
	v_mov_b32_e32 v161, v2
	s_cmp_eq_u32 s6, 0
	s_cbranch_scc1 .LBB0_157
.Lpeel_p1:
	s_add_u32 s40, s22, 0xfffc0080
	s_addc_u32 s41, s23, -1
	s_add_i32 s55, 0, 0x10000
	s_cmp_eq_u32 s49, 12
	s_cselect_b32 s61, s5, s41
	s_cselect_b32 s60, s7, s40
	s_cselect_b32 s41, s34, s47
	s_cselect_b32 s40, s35, s45
	s_add_i32 s57, 0, 0x14000
	v_add_u32_e32 v90, s55, v233
	v_add_u32_e32 v110, s57, v233
	ds_read_b128 v[74:77], v90
	ds_read_b128 v[78:81], v90 offset:1024
	ds_read_b128 v[82:85], v90 offset:2048
	ds_read_b128 v[90:93], v90 offset:3072
	ds_read_b128 v[94:97], v110
	ds_read_b128 v[98:101], v110 offset:1024
	ds_read_b128 v[102:105], v110 offset:2048
	ds_read_b128 v[110:113], v110 offset:3072
	v_lshl_add_u64 v[216:217], s[22:23], 0, v[188:189]
	s_add_i32 m0, s66, 0xc000
	ds_read_b128 v[162:165], v234
	ds_read_b128 v[166:169], v234 offset:1024
	ds_read_b128 v[192:195], v234 offset:2048
	ds_read_b128 v[196:199], v234 offset:3072
	ds_read_b128 v[200:203], v234 offset:4096
	ds_read_b128 v[204:207], v234 offset:5120
	ds_read_b128 v[208:211], v234 offset:6144
	ds_read_b128 v[212:215], v234 offset:7168
	global_load_lds_dwordx4 v[216:217], off
	v_lshl_add_u64 v[216:217], s[22:23], 0, v[190:191]
	s_add_i32 m0, s66, 0xe000
	s_nop 0
	global_load_lds_dwordx4 v[216:217], off
	s_waitcnt lgkmcnt(0)
	s_barrier
; #define PG8_STAGE(bufoff, gbase, voff) do { _Pragma("unroll") for (int _i = 0; _i < 2; ++_i) \
;         __builtin_amdgcn_global_load_lds((const unsigned*)((const char*)(gbase) + (voff)[_i]), (PG8_LAS unsigned*)(lds + (bufoff) + ldsw + _i * 8192), 16, 0, 0); } while (0)
; #define PG8_LDA(dst, b, h) do { _Pragma("unroll") for (int m = 0; m < 4; ++m) _Pragma("unroll") for (int k = 0; k < 2; ++k) dst[m][k] = *(const PG8_LAS bf16x8*)(lds + PG8_SA(b, h) + aoff + m * 2048 + k * 1024); } while (0)
; #define PG8_MMA(ai, bj, At, Bt) do { __builtin_amdgcn_s_setprio(1); _Pragma("unroll") for (int m = 0; m < 4; ++m) _Pragma("unroll") for (int n = 0; n < 2; ++n) _Pragma("unroll") for (int k = 0; k < 2; ++k) \
;         acc[ai][bj][m][n] = __builtin_amdgcn_mfma_f32_16x16x32_bf16(Bt[n][k], At[m][k], acc[ai][bj][m][n], 0, 0, 0); __builtin_amdgcn_s_setprio(0); } while (0)
; #define PG8_WAIT_V(n) asm volatile("s_waitcnt vmcnt(" #n ")" ::: "memory")
; #define PG8_WAIT_L(n) asm volatile("s_waitcnt lgkmcnt(" #n ")" ::: "memory")
; #define PG8_BAR __builtin_amdgcn_s_barrier()
; #define PG8_SCHED __builtin_amdgcn_sched_barrier(0)
; template <class Epi, class Sched, bool ALIGN_EPI = false, bool SP2 = false>
; __device__ __forceinline__ void gemm_phase(PG8_LAS unsigned char* lds, const Gemm g, const Sched& S, const Epi& E) {
;     ...
;             PG8_WAIT_V(8); PG8_WAIT_L(0); PG8_BAR; PG8_MMA(0, 0, At, B0); PG8_MMA(0, 1, At, B1); PG8_BAR; PG8_SCHED;
;             PG8_LDA(At, 0, 1); PG8_STAGE(PG8_SB(0, 0), b2, voffB); PG8_STAGE(PG8_SB(0, 1), b2 + hstep, voffB); PG8_STAGE(PG8_SA(0, 0), a2, voffA);
;             PG8_WAIT_V(8); PG8_WAIT_L(0); PG8_BAR; PG8_MMA(1, 0, At, B0); PG8_MMA(1, 1, At, B1); PG8_BAR; PG8_SCHED;
	s_setprio 1
	s_waitcnt lgkmcnt(0)
	v_mfma_f32_16x16x32_bf16 v[158:161], v[74:77], v[162:165], v[158:161]
	v_mfma_f32_16x16x32_bf16 v[154:157], v[82:85], v[162:165], v[154:157]
	v_mfma_f32_16x16x32_bf16 v[142:145], v[74:77], v[192:195], v[142:145]
	v_mfma_f32_16x16x32_bf16 v[138:141], v[82:85], v[192:195], v[138:141]
	v_mfma_f32_16x16x32_bf16 v[126:129], v[74:77], v[200:203], v[126:129]
	v_mfma_f32_16x16x32_bf16 v[122:125], v[82:85], v[200:203], v[122:125]
	v_mfma_f32_16x16x32_bf16 v[106:109], v[74:77], v[208:211], v[106:109]
	v_mfma_f32_16x16x32_bf16 v[86:89], v[82:85], v[208:211], v[86:89]
	v_mfma_f32_16x16x32_bf16 v[158:161], v[78:81], v[166:169], v[158:161]
	v_mfma_f32_16x16x32_bf16 v[154:157], v[90:93], v[166:169], v[154:157]
	v_mfma_f32_16x16x32_bf16 v[142:145], v[78:81], v[196:199], v[142:145]
	v_mfma_f32_16x16x32_bf16 v[138:141], v[90:93], v[196:199], v[138:141]
	v_mfma_f32_16x16x32_bf16 v[126:129], v[78:81], v[204:207], v[126:129]
	v_mfma_f32_16x16x32_bf16 v[122:125], v[90:93], v[204:207], v[122:125]
	v_mfma_f32_16x16x32_bf16 v[106:109], v[78:81], v[212:215], v[106:109]
	v_mfma_f32_16x16x32_bf16 v[86:89], v[90:93], v[212:215], v[86:89]
	s_setprio 0
	s_setprio 1
	v_mfma_f32_16x16x32_bf16 v[150:153], v[94:97], v[162:165], v[150:153]
	v_mfma_f32_16x16x32_bf16 v[146:149], v[102:105], v[162:165], v[146:149]
	v_mfma_f32_16x16x32_bf16 v[134:137], v[94:97], v[192:195], v[134:137]
	v_mfma_f32_16x16x32_bf16 v[130:133], v[102:105], v[192:195], v[130:133]
	v_mfma_f32_16x16x32_bf16 v[118:121], v[94:97], v[200:203], v[118:121]
	v_mfma_f32_16x16x32_bf16 v[114:117], v[102:105], v[200:203], v[114:117]
	v_mfma_f32_16x16x32_bf16 v[70:73], v[94:97], v[208:211], v[70:73]
	v_mfma_f32_16x16x32_bf16 v[66:69], v[102:105], v[208:211], v[66:69]
	v_mfma_f32_16x16x32_bf16 v[150:153], v[98:101], v[166:169], v[150:153]
	v_mfma_f32_16x16x32_bf16 v[146:149], v[110:113], v[166:169], v[146:149]
	v_mfma_f32_16x16x32_bf16 v[134:137], v[98:101], v[196:199], v[134:137]
	v_mfma_f32_16x16x32_bf16 v[130:133], v[110:113], v[196:199], v[130:133]
	v_mfma_f32_16x16x32_bf16 v[118:121], v[98:101], v[204:207], v[118:121]
	v_mfma_f32_16x16x32_bf16 v[114:117], v[110:113], v[204:207], v[114:117]
	v_mfma_f32_16x16x32_bf16 v[70:73], v[98:101], v[212:215], v[70:73]
	v_mfma_f32_16x16x32_bf16 v[66:69], v[110:113], v[212:215], v[66:69]
	s_setprio 0
	s_barrier
	s_add_i32 s55, s55, s65
	v_lshl_add_u64 v[216:217], s[40:41], 0, v[0:1]
	s_mov_b32 m0, s55
	ds_read_b128 v[162:165], v234 offset:16384
	ds_read_b128 v[166:169], v234 offset:17408
	ds_read_b128 v[192:195], v234 offset:18432
	ds_read_b128 v[196:199], v234 offset:19456
	ds_read_b128 v[200:203], v234 offset:20480
	ds_read_b128 v[204:207], v234 offset:21504
	ds_read_b128 v[208:211], v234 offset:22528
	ds_read_b128 v[212:215], v234 offset:23552
	global_load_lds_dwordx4 v[216:217], off
	s_add_i32 m0, s55, 0x2000
	s_add_u32 s62, s40, 0x40000
	v_lshl_add_u64 v[218:219], s[40:41], 0, v[186:187]
	s_addc_u32 s63, s41, 0
	s_add_i32 s55, s57, s65
	global_load_lds_dwordx4 v[218:219], off
	v_lshl_add_u64 v[236:237], s[62:63], 0, v[0:1]
	s_mov_b32 m0, s55
	v_lshl_add_u64 v[238:239], s[60:61], 0, v[184:185]
	global_load_lds_dwordx4 v[236:237], off
	v_lshl_add_u64 v[236:237], s[62:63], 0, v[186:187]
	s_add_i32 m0, s55, 0x2000
	s_nop 0
	global_load_lds_dwordx4 v[236:237], off
	v_lshl_add_u64 v[236:237], s[60:61], 0, v[182:183]
	s_mov_b32 m0, s66
	s_nop 0
	global_load_lds_dwordx4 v[236:237], off
	s_mov_b32 m0, s67
	s_nop 0
	global_load_lds_dwordx4 v[238:239], off
	s_waitcnt lgkmcnt(0)
	s_barrier
	s_setprio 1
	s_waitcnt lgkmcnt(0)
	v_mfma_f32_16x16x32_bf16 v[62:65], v[74:77], v[162:165], v[62:65]
	v_mfma_f32_16x16x32_bf16 v[58:61], v[82:85], v[162:165], v[58:61]
	v_mfma_f32_16x16x32_bf16 v[46:49], v[74:77], v[192:195], v[46:49]
	v_mfma_f32_16x16x32_bf16 v[42:45], v[82:85], v[192:195], v[42:45]
	v_mfma_f32_16x16x32_bf16 v[30:33], v[74:77], v[200:203], v[30:33]
	v_mfma_f32_16x16x32_bf16 v[26:29], v[82:85], v[200:203], v[26:29]
	v_mfma_f32_16x16x32_bf16 v[14:17], v[74:77], v[208:211], v[14:17]
	v_mfma_f32_16x16x32_bf16 v[10:13], v[82:85], v[208:211], v[10:13]
	v_mfma_f32_16x16x32_bf16 v[62:65], v[78:81], v[166:169], v[62:65]
	v_mfma_f32_16x16x32_bf16 v[58:61], v[90:93], v[166:169], v[58:61]
	v_mfma_f32_16x16x32_bf16 v[46:49], v[78:81], v[196:199], v[46:49]
	v_mfma_f32_16x16x32_bf16 v[42:45], v[90:93], v[196:199], v[42:45]
	v_mfma_f32_16x16x32_bf16 v[30:33], v[78:81], v[204:207], v[30:33]
	v_mfma_f32_16x16x32_bf16 v[26:29], v[90:93], v[204:207], v[26:29]
	v_mfma_f32_16x16x32_bf16 v[14:17], v[78:81], v[212:215], v[14:17]
	v_mfma_f32_16x16x32_bf16 v[10:13], v[90:93], v[212:215], v[10:13]
	s_setprio 0
	s_setprio 1
	v_mfma_f32_16x16x32_bf16 v[54:57], v[94:97], v[162:165], v[54:57]
	v_mfma_f32_16x16x32_bf16 v[50:53], v[102:105], v[162:165], v[50:53]
	v_mfma_f32_16x16x32_bf16 v[38:41], v[94:97], v[192:195], v[38:41]
	v_mfma_f32_16x16x32_bf16 v[34:37], v[102:105], v[192:195], v[34:37]
	v_mfma_f32_16x16x32_bf16 v[22:25], v[94:97], v[200:203], v[22:25]
	v_mfma_f32_16x16x32_bf16 v[18:21], v[102:105], v[200:203], v[18:21]
	v_mfma_f32_16x16x32_bf16 v[6:9], v[94:97], v[208:211], v[6:9]
	v_mfma_f32_16x16x32_bf16 v[2:5], v[102:105], v[208:211], v[2:5]
	v_mfma_f32_16x16x32_bf16 v[54:57], v[98:101], v[166:169], v[54:57]
	v_mfma_f32_16x16x32_bf16 v[50:53], v[110:113], v[166:169], v[50:53]
	v_mfma_f32_16x16x32_bf16 v[38:41], v[98:101], v[196:199], v[38:41]
	v_mfma_f32_16x16x32_bf16 v[34:37], v[110:113], v[196:199], v[34:37]
	v_mfma_f32_16x16x32_bf16 v[22:25], v[98:101], v[204:207], v[22:25]
	v_mfma_f32_16x16x32_bf16 v[18:21], v[110:113], v[204:207], v[18:21]
	v_mfma_f32_16x16x32_bf16 v[6:9], v[98:101], v[212:215], v[6:9]
	v_mfma_f32_16x16x32_bf16 v[2:5], v[110:113], v[212:215], v[2:5]
	s_setprio 0
	s_barrier
; #define PG8_STAGE(bufoff, gbase, voff) do { _Pragma("unroll") for (int _i = 0; _i < 2; ++_i) \
;         __builtin_amdgcn_global_load_lds((const unsigned*)((const char*)(gbase) + (voff)[_i]), (PG8_LAS unsigned*)(lds + (bufoff) + ldsw + _i * 8192), 16, 0, 0); } while (0)
; #define PG8_LDA(dst, b, h) do { _Pragma("unroll") for (int m = 0; m < 4; ++m) _Pragma("unroll") for (int k = 0; k < 2; ++k) dst[m][k] = *(const PG8_LAS bf16x8*)(lds + PG8_SA(b, h) + aoff + m * 2048 + k * 1024); } while (0)
; #define PG8_LDB(dst, b, h) do { _Pragma("unroll") for (int n = 0; n < 2; ++n) _Pragma("unroll") for (int k = 0; k < 2; ++k) dst[n][k] = *(const PG8_LAS bf16x8*)(lds + PG8_SB(b, h) + boff + n * 2048 + k * 1024); } while (0)
; #define PG8_MMA(ai, bj, At, Bt) do { __builtin_amdgcn_s_setprio(1); _Pragma("unroll") for (int m = 0; m < 4; ++m) _Pragma("unroll") for (int n = 0; n < 2; ++n) _Pragma("unroll") for (int k = 0; k < 2; ++k) \
;         acc[ai][bj][m][n] = __builtin_amdgcn_mfma_f32_16x16x32_bf16(Bt[n][k], At[m][k], acc[ai][bj][m][n], 0, 0, 0); __builtin_amdgcn_s_setprio(0); } while (0)
; #define PG8_WAIT_V(n) asm volatile("s_waitcnt vmcnt(" #n ")" ::: "memory")
; #define PG8_WAIT_L(n) asm volatile("s_waitcnt lgkmcnt(" #n ")" ::: "memory")
; #define PG8_BAR __builtin_amdgcn_s_barrier()
; #define PG8_SCHED __builtin_amdgcn_sched_barrier(0)
; template <class Epi, class Sched, bool ALIGN_EPI = false, bool SP2 = false>
; __device__ __forceinline__ void gemm_phase(PG8_LAS unsigned char* lds, const Gemm g, const Sched& S, const Epi& E) {
;     ...
;             PG8_LDB(B0, 1, 0); PG8_LDB(B1, 1, 1); PG8_SCHED; PG8_LDA(At, 1, 0); PG8_STAGE(PG8_SA(0, 1), a2 + hstep, voffA);
;             PG8_WAIT_V(8); PG8_WAIT_L(0); PG8_BAR; PG8_MMA(0, 0, At, B0); PG8_MMA(0, 1, At, B1); PG8_BAR; PG8_SCHED;
	s_add_i32 s55, 0, 0x18000
	s_add_i32 s57, 0, 0x1c000
	v_add_u32_e32 v90, s55, v233
	v_add_u32_e32 v110, s57, v233
	ds_read_b128 v[74:77], v90
	ds_read_b128 v[78:81], v90 offset:1024
	ds_read_b128 v[82:85], v90 offset:2048
	ds_read_b128 v[90:93], v90 offset:3072
	ds_read_b128 v[94:97], v110
	ds_read_b128 v[98:101], v110 offset:1024
	ds_read_b128 v[102:105], v110 offset:2048
	ds_read_b128 v[110:113], v110 offset:3072
	s_add_u32 s60, s60, 0x40000
	s_addc_u32 s61, s61, 0
	s_mov_b32 m0, s70
	v_lshl_add_u64 v[240:241], s[60:61], 0, v[182:183]
	ds_read_b128 v[162:165], v234 offset:32768
	ds_read_b128 v[166:169], v234 offset:33792
	ds_read_b128 v[192:195], v234 offset:34816
	ds_read_b128 v[196:199], v234 offset:35840
	ds_read_b128 v[200:203], v234 offset:36864
	ds_read_b128 v[204:207], v234 offset:37888
	ds_read_b128 v[208:211], v234 offset:38912
	ds_read_b128 v[212:215], v234 offset:39936
	global_load_lds_dwordx4 v[240:241], off
	v_lshl_add_u64 v[240:241], s[60:61], 0, v[184:185]
	s_mov_b32 m0, s71
	s_nop 0
	global_load_lds_dwordx4 v[240:241], off
	s_waitcnt vmcnt(8)
	s_waitcnt lgkmcnt(0)
	s_barrier
	s_setprio 1
	s_waitcnt lgkmcnt(0)
	v_mfma_f32_16x16x32_bf16 v[158:161], v[74:77], v[162:165], v[158:161]
	v_mfma_f32_16x16x32_bf16 v[154:157], v[82:85], v[162:165], v[154:157]
	v_mfma_f32_16x16x32_bf16 v[142:145], v[74:77], v[192:195], v[142:145]
	v_mfma_f32_16x16x32_bf16 v[138:141], v[82:85], v[192:195], v[138:141]
	v_mfma_f32_16x16x32_bf16 v[126:129], v[74:77], v[200:203], v[126:129]
	v_mfma_f32_16x16x32_bf16 v[122:125], v[82:85], v[200:203], v[122:125]
	v_mfma_f32_16x16x32_bf16 v[106:109], v[74:77], v[208:211], v[106:109]
	v_mfma_f32_16x16x32_bf16 v[86:89], v[82:85], v[208:211], v[86:89]
	v_mfma_f32_16x16x32_bf16 v[158:161], v[78:81], v[166:169], v[158:161]
	v_mfma_f32_16x16x32_bf16 v[154:157], v[90:93], v[166:169], v[154:157]
	v_mfma_f32_16x16x32_bf16 v[142:145], v[78:81], v[196:199], v[142:145]
	v_mfma_f32_16x16x32_bf16 v[138:141], v[90:93], v[196:199], v[138:141]
	v_mfma_f32_16x16x32_bf16 v[126:129], v[78:81], v[204:207], v[126:129]
	v_mfma_f32_16x16x32_bf16 v[122:125], v[90:93], v[204:207], v[122:125]
	v_mfma_f32_16x16x32_bf16 v[106:109], v[78:81], v[212:215], v[106:109]
	v_mfma_f32_16x16x32_bf16 v[86:89], v[90:93], v[212:215], v[86:89]
	s_setprio 0
	s_setprio 1
	v_mfma_f32_16x16x32_bf16 v[150:153], v[94:97], v[162:165], v[150:153]
	v_mfma_f32_16x16x32_bf16 v[146:149], v[102:105], v[162:165], v[146:149]
	v_mfma_f32_16x16x32_bf16 v[134:137], v[94:97], v[192:195], v[134:137]
	v_mfma_f32_16x16x32_bf16 v[130:133], v[102:105], v[192:195], v[130:133]
	v_mfma_f32_16x16x32_bf16 v[118:121], v[94:97], v[200:203], v[118:121]
	v_mfma_f32_16x16x32_bf16 v[114:117], v[102:105], v[200:203], v[114:117]
	v_mfma_f32_16x16x32_bf16 v[70:73], v[94:97], v[208:211], v[70:73]
	v_mfma_f32_16x16x32_bf16 v[66:69], v[102:105], v[208:211], v[66:69]
	v_mfma_f32_16x16x32_bf16 v[150:153], v[98:101], v[166:169], v[150:153]
	v_mfma_f32_16x16x32_bf16 v[146:149], v[110:113], v[166:169], v[146:149]
	v_mfma_f32_16x16x32_bf16 v[134:137], v[98:101], v[196:199], v[134:137]
	v_mfma_f32_16x16x32_bf16 v[130:133], v[110:113], v[196:199], v[130:133]
	v_mfma_f32_16x16x32_bf16 v[118:121], v[98:101], v[204:207], v[118:121]
	v_mfma_f32_16x16x32_bf16 v[114:117], v[110:113], v[204:207], v[114:117]
	v_mfma_f32_16x16x32_bf16 v[70:73], v[98:101], v[212:215], v[70:73]
	v_mfma_f32_16x16x32_bf16 v[66:69], v[110:113], v[212:215], v[66:69]
	s_setprio 0
	s_barrier
; #define PG8_STAGE(bufoff, gbase, voff) do { _Pragma("unroll") for (int _i = 0; _i < 2; ++_i) \
;         __builtin_amdgcn_global_load_lds((const unsigned*)((const char*)(gbase) + (voff)[_i]), (PG8_LAS unsigned*)(lds + (bufoff) + ldsw + _i * 8192), 16, 0, 0); } while (0)
; #define PG8_LDA(dst, b, h) do { _Pragma("unroll") for (int m = 0; m < 4; ++m) _Pragma("unroll") for (int k = 0; k < 2; ++k) dst[m][k] = *(const PG8_LAS bf16x8*)(lds + PG8_SA(b, h) + aoff + m * 2048 + k * 1024); } while (0)
; #define PG8_MMA(ai, bj, At, Bt) do { __builtin_amdgcn_s_setprio(1); _Pragma("unroll") for (int m = 0; m < 4; ++m) _Pragma("unroll") for (int n = 0; n < 2; ++n) _Pragma("unroll") for (int k = 0; k < 2; ++k) \
;         acc[ai][bj][m][n] = __builtin_amdgcn_mfma_f32_16x16x32_bf16(Bt[n][k], At[m][k], acc[ai][bj][m][n], 0, 0, 0); __builtin_amdgcn_s_setprio(0); } while (0)
; #define PG8_WAIT_V(n) asm volatile("s_waitcnt vmcnt(" #n ")" ::: "memory")
; #define PG8_WAIT_L(n) asm volatile("s_waitcnt lgkmcnt(" #n ")" ::: "memory")
; #define PG8_BAR __builtin_amdgcn_s_barrier()
; #define PG8_SCHED __builtin_amdgcn_sched_barrier(0)
; template <class Epi, class Sched, bool ALIGN_EPI = false, bool SP2 = false>
; __device__ __forceinline__ void gemm_phase(PG8_LAS unsigned char* lds, const Gemm g, const Sched& S, const Epi& E) {
;     ...
;         for (int t = 0; t < nt; t += 2) {
;     ...
;             PG8_LDA(At, 1, 1); PG8_STAGE(PG8_SB(1, 0), b3, voffB); PG8_STAGE(PG8_SB(1, 1), b3 + hstep, voffB); PG8_STAGE(PG8_SA(1, 0), a3, voffA);
;             PG8_WAIT_V(8); PG8_WAIT_L(0); PG8_BAR; PG8_MMA(1, 0, At, B0); PG8_MMA(1, 1, At, B1); PG8_BAR; PG8_SCHED;
	s_add_i32 s55, s55, s65
	v_lshl_add_u64 v[216:217], v[216:217], 0, s[36:37]
	s_mov_b32 m0, s55
	ds_read_b128 v[162:165], v234 offset:49152
	ds_read_b128 v[166:169], v234 offset:50176
	ds_read_b128 v[192:195], v234 offset:51200
	ds_read_b128 v[196:199], v234 offset:52224
	ds_read_b128 v[200:203], v234 offset:53248
	ds_read_b128 v[204:207], v234 offset:54272
	ds_read_b128 v[208:211], v234 offset:55296
	ds_read_b128 v[212:215], v234 offset:56320
	global_load_lds_dwordx4 v[216:217], off
	s_add_i32 m0, s55, 0x2000
	s_add_u32 s40, s40, 0x40080
	v_lshl_add_u64 v[216:217], v[218:219], 0, s[36:37]
	s_addc_u32 s41, s41, 0
	s_add_i32 s55, s57, s65
	global_load_lds_dwordx4 v[216:217], off
	v_lshl_add_u64 v[216:217], s[40:41], 0, v[0:1]
	s_mov_b32 m0, s55
	s_nop 0
	global_load_lds_dwordx4 v[216:217], off
	v_lshl_add_u64 v[216:217], s[40:41], 0, v[186:187]
	s_add_i32 m0, s55, 0x2000
	s_nop 0
	global_load_lds_dwordx4 v[216:217], off
	v_lshl_add_u64 v[216:217], v[236:237], 0, s[36:37]
	s_mov_b32 m0, s76
	s_nop 0
	global_load_lds_dwordx4 v[216:217], off
	v_lshl_add_u64 v[216:217], v[238:239], 0, s[36:37]
	s_mov_b32 m0, s77
	s_nop 0
	global_load_lds_dwordx4 v[216:217], off
	s_waitcnt vmcnt(8)
	s_waitcnt lgkmcnt(0)
	s_barrier
	s_setprio 1
	s_waitcnt lgkmcnt(0)
	v_mfma_f32_16x16x32_bf16 v[62:65], v[74:77], v[162:165], v[62:65]
	v_mfma_f32_16x16x32_bf16 v[58:61], v[82:85], v[162:165], v[58:61]
	v_mfma_f32_16x16x32_bf16 v[46:49], v[74:77], v[192:195], v[46:49]
	v_mfma_f32_16x16x32_bf16 v[42:45], v[82:85], v[192:195], v[42:45]
	v_mfma_f32_16x16x32_bf16 v[30:33], v[74:77], v[200:203], v[30:33]
	v_mfma_f32_16x16x32_bf16 v[26:29], v[82:85], v[200:203], v[26:29]
	v_mfma_f32_16x16x32_bf16 v[14:17], v[74:77], v[208:211], v[14:17]
	v_mfma_f32_16x16x32_bf16 v[10:13], v[82:85], v[208:211], v[10:13]
	v_mfma_f32_16x16x32_bf16 v[62:65], v[78:81], v[166:169], v[62:65]
	v_mfma_f32_16x16x32_bf16 v[58:61], v[90:93], v[166:169], v[58:61]
	v_mfma_f32_16x16x32_bf16 v[46:49], v[78:81], v[196:199], v[46:49]
	v_mfma_f32_16x16x32_bf16 v[42:45], v[90:93], v[196:199], v[42:45]
	v_mfma_f32_16x16x32_bf16 v[30:33], v[78:81], v[204:207], v[30:33]
	v_mfma_f32_16x16x32_bf16 v[26:29], v[90:93], v[204:207], v[26:29]
	v_mfma_f32_16x16x32_bf16 v[14:17], v[78:81], v[212:215], v[14:17]
	v_mfma_f32_16x16x32_bf16 v[10:13], v[90:93], v[212:215], v[10:13]
	s_setprio 0
	s_setprio 1
	v_mfma_f32_16x16x32_bf16 v[54:57], v[94:97], v[162:165], v[54:57]
	v_mfma_f32_16x16x32_bf16 v[50:53], v[102:105], v[162:165], v[50:53]
	v_mfma_f32_16x16x32_bf16 v[38:41], v[94:97], v[192:195], v[38:41]
	v_mfma_f32_16x16x32_bf16 v[34:37], v[102:105], v[192:195], v[34:37]
	v_mfma_f32_16x16x32_bf16 v[22:25], v[94:97], v[200:203], v[22:25]
	v_mfma_f32_16x16x32_bf16 v[18:21], v[102:105], v[200:203], v[18:21]
	v_mfma_f32_16x16x32_bf16 v[6:9], v[94:97], v[208:211], v[6:9]
	v_mfma_f32_16x16x32_bf16 v[2:5], v[102:105], v[208:211], v[2:5]
	v_mfma_f32_16x16x32_bf16 v[54:57], v[98:101], v[166:169], v[54:57]
	v_mfma_f32_16x16x32_bf16 v[50:53], v[110:113], v[166:169], v[50:53]
	v_mfma_f32_16x16x32_bf16 v[38:41], v[98:101], v[196:199], v[38:41]
	v_mfma_f32_16x16x32_bf16 v[34:37], v[110:113], v[196:199], v[34:37]
	v_mfma_f32_16x16x32_bf16 v[22:25], v[98:101], v[204:207], v[22:25]
	v_mfma_f32_16x16x32_bf16 v[18:21], v[110:113], v[204:207], v[18:21]
	v_mfma_f32_16x16x32_bf16 v[6:9], v[98:101], v[212:215], v[6:9]
	v_mfma_f32_16x16x32_bf16 v[2:5], v[110:113], v[212:215], v[2:5]
	s_setprio 0
	s_barrier
	s_add_i32 s49, s49, 2
	s_add_u32 s22, s22, 0x100
	s_addc_u32 s23, s23, 0
	s_add_u32 s45, s45, 0x100
	s_addc_u32 s47, s47, 0
	s_cmp_gt_u32 s49, 13
	s_cbranch_scc0 .LBB0_157
	s_branch .Lafter_157

; #define PG8_BAR __builtin_amdgcn_s_barrier()
; template <class Epi, class Sched, bool ALIGN_EPI = false, bool SP2 = false>
; __device__ __forceinline__ void gemm_phase(PG8_LAS unsigned char* lds, const Gemm g, const Sched& S, const Epi& E) {
;     ...
;         if constexpr (ALIGN_EPI) { if (wr == 0) PG8_BAR; }
.Lafter_157:
	s_and_b64 vcc, exec, s[12:13]
	s_cbranch_vccz .LBB0_160
	s_barrier

;     __device__ __forceinline__ void operator()(const f32x4 (&acc)[2][2][4][2], const pg8::Unit& u, int wr, int wc, int fr, int fq) const {
;     ...
;         } else if (cat == 5) {
;             float* HF = (float*)(ws + WS_HF);
; #pragma unroll
;             for (int ai = 0; ai < 2; ++ai)
; #pragma unroll
;                 for (int m = 0; m < 4; ++m) { const int r = rowb + ai * 128 + m * 16; const float sc = rs[ai][m];
; #pragma unroll
;                     for (int bj = 0; bj < 2; ++bj)
; #pragma unroll
;                         for (int n = 0; n < 2; ++n) *(f32x4*)(HF + (size_t)r * 512 + cb + bj * 128 + n * 4) = acc[ai][bj][m][n] * sc; }
.LBB0_176:
	s_or_b64 exec, exec, s[60:61]
	s_waitcnt vmcnt(0)
	s_mov_b64 s[42:43], 0
.LBB0_177:
	s_andn2_b64 vcc, exec, s[42:43]
	s_cbranch_vccnz .LBB0_179
	v_ashrrev_i32_e32 v203, 31, v202
	v_ashrrev_i32_e32 v193, 31, v192
	v_lshl_add_u64 v[162:163], v[202:203], 2, s[22:23]
	v_lshlrev_b64 v[164:165], 11, v[192:193]
	v_lshl_add_u64 v[162:163], v[162:163], 0, v[164:165]
	v_add_co_u32_e32 v204, vcc, 0x29f08000, v162
	s_mov_b64 s[0:1], 0x29f08000
	s_waitcnt lgkmcnt(0)
	v_pk_mul_f32 v[164:165], v[158:159], v[200:201] op_sel_hi:[1,0]
	v_pk_mul_f32 v[166:167], v[160:161], v[200:201] op_sel_hi:[1,0]
	v_addc_co_u32_e32 v205, vcc, 0, v163, vcc
	v_lshl_add_u64 v[168:169], v[162:163], 0, s[0:1]
	global_store_dwordx4 v[204:205], v[164:167], off
	s_mov_b32 s5, 0x29f10000
	v_add_co_u32_e32 v204, vcc, s5, v162
	v_pk_mul_f32 v[164:165], v[154:155], v[200:201] op_sel_hi:[1,0]
	v_pk_mul_f32 v[166:167], v[156:157], v[200:201] op_sel_hi:[1,0]
	global_store_dwordx4 v[168:169], v[164:167], off offset:16
	s_mov_b64 s[6:7], 0x29f10000
	v_addc_co_u32_e32 v205, vcc, 0, v163, vcc
	v_pk_mul_f32 v[164:165], v[150:151], v[200:201] op_sel_hi:[1,0]
	v_pk_mul_f32 v[166:167], v[152:153], v[200:201] op_sel_hi:[1,0]
	global_store_dwordx4 v[168:169], v[164:167], off offset:512
	s_mov_b32 s5, 0x29f18000
	s_nop 0
	v_pk_mul_f32 v[164:165], v[146:147], v[200:201] op_sel_hi:[1,0]
	v_pk_mul_f32 v[166:167], v[148:149], v[200:201] op_sel_hi:[1,0]
	global_store_dwordx4 v[168:169], v[164:167], off offset:528
	v_lshl_add_u64 v[168:169], v[162:163], 0, s[6:7]
	s_mov_b64 s[6:7], 0x29f18000
	v_pk_mul_f32 v[164:165], v[142:143], v[200:201] op_sel:[0,1]
	v_pk_mul_f32 v[166:167], v[144:145], v[200:201] op_sel:[0,1]
	global_store_dwordx4 v[204:205], v[164:167], off
	v_add_co_u32_e32 v204, vcc, s5, v162
	s_nop 0
	v_pk_mul_f32 v[164:165], v[138:139], v[200:201] op_sel:[0,1]
	v_pk_mul_f32 v[166:167], v[140:141], v[200:201] op_sel:[0,1]
	global_store_dwordx4 v[168:169], v[164:167], off offset:16
	v_addc_co_u32_e32 v205, vcc, 0, v163, vcc
	s_nop 0
	v_pk_mul_f32 v[164:165], v[134:135], v[200:201] op_sel:[0,1]
	v_pk_mul_f32 v[166:167], v[136:137], v[200:201] op_sel:[0,1]
	global_store_dwordx4 v[168:169], v[164:167], off offset:512
	s_mov_b32 s5, 0x29f20000
	s_nop 0
	v_pk_mul_f32 v[164:165], v[130:131], v[200:201] op_sel:[0,1]
	v_pk_mul_f32 v[166:167], v[132:133], v[200:201] op_sel:[0,1]
	global_store_dwordx4 v[168:169], v[164:167], off offset:528
	v_lshl_add_u64 v[168:169], v[162:163], 0, s[6:7]
	s_mov_b64 s[6:7], 0x29f20000
	v_pk_mul_f32 v[164:165], v[126:127], v[198:199] op_sel_hi:[1,0]
	v_pk_mul_f32 v[166:167], v[128:129], v[198:199] op_sel_hi:[1,0]
	global_store_dwordx4 v[204:205], v[164:167], off
	v_add_co_u32_e32 v204, vcc, s5, v162
	s_nop 0
	v_pk_mul_f32 v[164:165], v[122:123], v[198:199] op_sel_hi:[1,0]
	v_pk_mul_f32 v[166:167], v[124:125], v[198:199] op_sel_hi:[1,0]
	global_store_dwordx4 v[168:169], v[164:167], off offset:16
	v_addc_co_u32_e32 v205, vcc, 0, v163, vcc
	s_nop 0
	v_pk_mul_f32 v[164:165], v[118:119], v[198:199] op_sel_hi:[1,0]
	v_pk_mul_f32 v[166:167], v[120:121], v[198:199] op_sel_hi:[1,0]
	global_store_dwordx4 v[168:169], v[164:167], off offset:512
	s_mov_b32 s5, 0x29f48000
	s_nop 0
	v_pk_mul_f32 v[164:165], v[114:115], v[198:199] op_sel_hi:[1,0]
	v_pk_mul_f32 v[166:167], v[116:117], v[198:199] op_sel_hi:[1,0]
	global_store_dwordx4 v[168:169], v[164:167], off offset:528
	v_lshl_add_u64 v[168:169], v[162:163], 0, s[6:7]
	s_mov_b64 s[6:7], 0x29f48000
	v_pk_mul_f32 v[164:165], v[106:107], v[198:199] op_sel:[0,1]
	v_pk_mul_f32 v[166:167], v[108:109], v[198:199] op_sel:[0,1]
	global_store_dwordx4 v[204:205], v[164:167], off
	v_add_co_u32_e32 v204, vcc, s5, v162
	s_nop 0
	v_pk_mul_f32 v[164:165], v[86:87], v[198:199] op_sel:[0,1]
	v_pk_mul_f32 v[166:167], v[88:89], v[198:199] op_sel:[0,1]
	global_store_dwordx4 v[168:169], v[164:167], off offset:16
	v_addc_co_u32_e32 v205, vcc, 0, v163, vcc
	s_nop 0
	v_pk_mul_f32 v[164:165], v[70:71], v[198:199] op_sel:[0,1]
;     __device__ __forceinline__ void operator()(const f32x4 (&acc)[2][2][4][2], const pg8::Unit& u, int wr, int wc, int fr, int fq) const {
;     ...
;         } else if (cat == 5) {
;             float* HF = (float*)(ws + WS_HF);
; #pragma unroll
;             for (int ai = 0; ai < 2; ++ai)
; #pragma unroll
;                 for (int m = 0; m < 4; ++m) { const int r = rowb + ai * 128 + m * 16; const float sc = rs[ai][m];
; #pragma unroll
;                     for (int bj = 0; bj < 2; ++bj)
; #pragma unroll
;                         for (int n = 0; n < 2; ++n) *(f32x4*)(HF + (size_t)r * 512 + cb + bj * 128 + n * 4) = acc[ai][bj][m][n] * sc; }
	v_pk_mul_f32 v[166:167], v[72:73], v[198:199] op_sel:[0,1]
	global_store_dwordx4 v[168:169], v[164:167], off offset:512
	s_mov_b32 s5, 0x29f50000
	s_nop 0
	v_pk_mul_f32 v[164:165], v[66:67], v[198:199] op_sel:[0,1]
	v_pk_mul_f32 v[166:167], v[68:69], v[198:199] op_sel:[0,1]
	global_store_dwordx4 v[168:169], v[164:167], off offset:528
	v_lshl_add_u64 v[168:169], v[162:163], 0, s[6:7]
	s_mov_b64 s[6:7], 0x29f50000
	v_pk_mul_f32 v[164:165], v[62:63], v[196:197] op_sel_hi:[1,0]
	v_pk_mul_f32 v[166:167], v[64:65], v[196:197] op_sel_hi:[1,0]
	global_store_dwordx4 v[204:205], v[164:167], off
	v_add_co_u32_e32 v204, vcc, s5, v162
	s_nop 0
	v_pk_mul_f32 v[164:165], v[58:59], v[196:197] op_sel_hi:[1,0]
	v_pk_mul_f32 v[166:167], v[60:61], v[196:197] op_sel_hi:[1,0]
	global_store_dwordx4 v[168:169], v[164:167], off offset:16
	v_addc_co_u32_e32 v205, vcc, 0, v163, vcc
	s_nop 0
	v_pk_mul_f32 v[164:165], v[54:55], v[196:197] op_sel_hi:[1,0]
	v_pk_mul_f32 v[166:167], v[56:57], v[196:197] op_sel_hi:[1,0]
	global_store_dwordx4 v[168:169], v[164:167], off offset:512
	s_mov_b32 s5, 0x29f58000
	s_nop 0
	v_pk_mul_f32 v[164:165], v[50:51], v[196:197] op_sel_hi:[1,0]
	v_pk_mul_f32 v[166:167], v[52:53], v[196:197] op_sel_hi:[1,0]
	global_store_dwordx4 v[168:169], v[164:167], off offset:528
	v_lshl_add_u64 v[168:169], v[162:163], 0, s[6:7]
	s_mov_b64 s[6:7], 0x29f58000
	v_pk_mul_f32 v[164:165], v[46:47], v[196:197] op_sel:[0,1]
	v_pk_mul_f32 v[166:167], v[48:49], v[196:197] op_sel:[0,1]
	global_store_dwordx4 v[204:205], v[164:167], off
	v_add_co_u32_e32 v204, vcc, s5, v162
	s_nop 0
	v_pk_mul_f32 v[164:165], v[42:43], v[196:197] op_sel:[0,1]
	v_pk_mul_f32 v[166:167], v[44:45], v[196:197] op_sel:[0,1]
	global_store_dwordx4 v[168:169], v[164:167], off offset:16
	v_addc_co_u32_e32 v205, vcc, 0, v163, vcc
	s_nop 0
	v_pk_mul_f32 v[164:165], v[38:39], v[196:197] op_sel:[0,1]
	v_pk_mul_f32 v[166:167], v[40:41], v[196:197] op_sel:[0,1]
	global_store_dwordx4 v[168:169], v[164:167], off offset:512
	s_mov_b32 s5, 0x29f60000
	s_nop 0
	v_pk_mul_f32 v[164:165], v[34:35], v[196:197] op_sel:[0,1]
	v_pk_mul_f32 v[166:167], v[36:37], v[196:197] op_sel:[0,1]
	global_store_dwordx4 v[168:169], v[164:167], off offset:528
	v_lshl_add_u64 v[168:169], v[162:163], 0, s[6:7]
	s_mov_b64 s[6:7], 0x29f60000
	v_pk_mul_f32 v[164:165], v[30:31], v[194:195] op_sel_hi:[1,0]
	v_pk_mul_f32 v[166:167], v[32:33], v[194:195] op_sel_hi:[1,0]
	global_store_dwordx4 v[204:205], v[164:167], off
	s_nop 1
	v_pk_mul_f32 v[164:165], v[26:27], v[194:195] op_sel_hi:[1,0]
	v_pk_mul_f32 v[166:167], v[28:29], v[194:195] op_sel_hi:[1,0]
	global_store_dwordx4 v[168:169], v[164:167], off offset:16
	s_nop 1
	v_pk_mul_f32 v[164:165], v[22:23], v[194:195] op_sel_hi:[1,0]
	v_pk_mul_f32 v[166:167], v[24:25], v[194:195] op_sel_hi:[1,0]
	global_store_dwordx4 v[168:169], v[164:167], off offset:512
	s_nop 1
	v_pk_mul_f32 v[164:165], v[18:19], v[194:195] op_sel_hi:[1,0]
	v_pk_mul_f32 v[166:167], v[20:21], v[194:195] op_sel_hi:[1,0]
	global_store_dwordx4 v[168:169], v[164:167], off offset:528
	v_lshl_add_u64 v[168:169], v[162:163], 0, s[6:7]
	v_add_co_u32_e32 v162, vcc, s5, v162
	v_pk_mul_f32 v[164:165], v[14:15], v[194:195] op_sel:[0,1]
	v_pk_mul_f32 v[166:167], v[16:17], v[194:195] op_sel:[0,1]
	v_addc_co_u32_e32 v163, vcc, 0, v163, vcc
	global_store_dwordx4 v[162:163], v[164:167], off
	v_pk_mul_f32 v[162:163], v[10:11], v[194:195] op_sel:[0,1]
	s_nop 0
	v_pk_mul_f32 v[164:165], v[12:13], v[194:195] op_sel:[0,1]
	global_store_dwordx4 v[168:169], v[162:165], off offset:16
	s_nop 1
	v_pk_mul_f32 v[162:163], v[6:7], v[194:195] op_sel:[0,1]
	v_pk_mul_f32 v[164:165], v[8:9], v[194:195] op_sel:[0,1]
	global_store_dwordx4 v[168:169], v[162:165], off offset:512
	s_nop 1
	v_pk_mul_f32 v[162:163], v[2:3], v[194:195] op_sel:[0,1]
	v_pk_mul_f32 v[164:165], v[4:5], v[194:195] op_sel:[0,1]
	global_store_dwordx4 v[168:169], v[162:165], off offset:528
	s_waitcnt vmcnt(32)

;     __device__ __forceinline__ void operator()(const f32x4 (&acc)[2][2][4][2], const pg8::Unit& u, int wr, int wc, int fr, int fq) const {
;     ...
;         } else if (cat == 1 || cat == 2) {
; #pragma unroll
;             for (int ai = 0; ai < 2; ++ai)
; #pragma unroll
;                 for (int m = 0; m < 4; ++m) { const int r = rowb + ai * 128 + m * 16; const float sc = rs[ai][m];
;                     float* fo; bf16_t* bo;
;                     if (!samp) { fo = out + (cat == 1 ? OFF_KP : OFF_VP) + ((size_t)layer * MP + r) * 512; bo = (bf16_t*)(ws + (cat == 1 ? WS_KBP : WS_VTP)) + (size_t)r * 512; }
;                     else { const int q = r - MP; fo = out + (cat == 1 ? OFF_KS : OFF_VS) + ((size_t)layer * MS + q) * 512; bo = (bf16_t*)(ws + (cat == 1 ? WS_KBS : WS_VTS)) + ((size_t)layer * KSROWS + (size_t)((q >> 6) * SKV + PAST + (q & 63))) * 512; }
; #pragma unroll
;                     for (int bj = 0; bj < 2; ++bj) { u32x4 w;
; #pragma unroll
;                         for (int n = 0; n < 2; ++n) { const f32x4 v = acc[ai][bj][m][n] * sc; *(f32x4*)(fo + cb + bj * 128 + 4 * n) = v; w[2 * n] = pk2(v[0], v[1]); w[2 * n + 1] = pk2(v[2], v[3]); }
;                         *(u32x4*)(bo + cb + bj * 128) = w; } }
.LBB0_213:
	s_add_u32 s6, s22, s42
	s_addc_u32 s7, s23, s43
	v_lshlrev_b64 v[164:165], 10, v[164:165]
	v_lshl_add_u64 v[164:165], s[6:7], 0, v[164:165]
	v_lshl_add_u64 v[168:169], v[202:203], 2, v[162:163]
	v_lshl_add_u64 v[204:205], v[202:203], 1, v[164:165]
	v_pk_mul_f32 v[162:163], v[14:15], v[194:195] op_sel:[0,1]
	v_pk_mul_f32 v[164:165], v[16:17], v[194:195] op_sel:[0,1]
	global_store_dwordx4 v[168:169], v[162:165], off
	v_pk_mul_f32 v[166:167], v[12:13], v[194:195] op_sel:[0,1]
	s_nop 0
	v_cvt_pk_bf16_f32 v162, v162, v163
	v_cvt_pk_bf16_f32 v163, v164, v165
	v_pk_mul_f32 v[164:165], v[10:11], v[194:195] op_sel:[0,1]
	global_store_dwordx4 v[168:169], v[164:167], off offset:16
	s_nop 1
	v_cvt_pk_bf16_f32 v164, v164, v165
	v_cvt_pk_bf16_f32 v165, v166, v167
	global_store_dwordx4 v[204:205], v[162:165], off
	v_pk_mul_f32 v[166:167], v[4:5], v[194:195] op_sel:[0,1]
	s_nop 0
	v_pk_mul_f32 v[162:163], v[6:7], v[194:195] op_sel:[0,1]
	v_pk_mul_f32 v[164:165], v[8:9], v[194:195] op_sel:[0,1]
	global_store_dwordx4 v[168:169], v[162:165], off offset:512
	s_nop 1
	v_cvt_pk_bf16_f32 v162, v162, v163
	v_cvt_pk_bf16_f32 v163, v164, v165
	v_pk_mul_f32 v[164:165], v[2:3], v[194:195] op_sel:[0,1]
	global_store_dwordx4 v[168:169], v[164:167], off offset:528
	s_nop 1
	v_cvt_pk_bf16_f32 v164, v164, v165
	v_cvt_pk_bf16_f32 v165, v166, v167
	global_store_dwordx4 v[204:205], v[162:165], off offset:256
	s_waitcnt vmcnt(48)

; __device__ __forceinline__ float fsilu(float x) { return x * __builtin_amdgcn_rcpf(1.f + __expf(-x)); }
;     __device__ __forceinline__ void operator()(const f32x4 (&acc)[2][2][4][2], const pg8::Unit& u, int wr, int wc, int fr, int fq) const {
;     ...
;                     for (int bj = 0; bj < 2; ++bj) { u32x4 w;
; #pragma unroll
;                         for (int n = 0; n < 2; ++n) { f32x4 v = acc[ai][bj][m][n] * sc;
;                             if (cat == 0) v = v * QSCALE; else if (cat != 6) { v[0] = fsilu(v[0]); v[1] = fsilu(v[1]); v[2] = fsilu(v[2]); v[3] = fsilu(v[3]); }
;                             w[2 * n] = pk2(v[0], v[1]); w[2 * n + 1] = pk2(v[2], v[3]); }
;                         *(u32x4*)(base + (size_t)r * pitch + cb + bj * 128) = w; } }
;     ...
;         if (hasn) {
; #pragma unroll
;             for (int q = 0; q < 8; ++q) { float s_ = (np[q][0] + np[q][1]) + (np[q][2] + np[q][3]); s_ += __shfl_xor(s_, 16); s_ += __shfl_xor(s_, 32);
;                 if (fq == 0) slot[q * 16 + fr] = rsqrtf(s_ * (1.0f / 1024.0f) + EPS); }
;         }
.LBB0_425:
	v_cvt_pk_bf16_f32 v2, v6, v7
	v_cvt_pk_bf16_f32 v3, v8, v9
	v_cvt_pk_bf16_f32 v4, v10, v11
	v_cvt_pk_bf16_f32 v5, v12, v13
	global_store_dwordx4 v[14:15], v[2:5], off offset:256
	s_and_b64 vcc, exec, s[40:41]
	s_mov_b64 s[22:23], -1
	s_cbranch_vccnz .LBB0_149
	s_waitcnt vmcnt(16)
.LBB0_426:
	v_and_b32_e32 v3, 64, v222
	v_xor_b32_e32 v2, 16, v222
	v_add_u32_e32 v3, 64, v3
	v_cmp_lt_i32_e32 vcc, v2, v3
	v_add_f32_e32 v4, v110, v111
	v_add_f32_e32 v5, v112, v113
	v_cndmask_b32_e32 v2, v222, v2, vcc
	v_lshlrev_b32_e32 v2, 2, v2
	v_add_f32_e32 v4, v4, v5
	ds_bpermute_b32 v5, v2, v4
	v_xor_b32_e32 v6, 32, v222
	v_cmp_lt_i32_e32 vcc, v6, v3
	s_waitcnt lgkmcnt(0)
	v_add_f32_e32 v4, v4, v5
	v_cndmask_b32_e32 v3, v222, v6, vcc
	v_lshlrev_b32_e32 v3, 2, v3
	ds_bpermute_b32 v5, v3, v4
	v_cmp_eq_u32_e32 vcc, 0, v236
	s_and_saveexec_b64 s[22:23], vcc
	s_cbranch_execz .LBB0_428
	s_waitcnt lgkmcnt(0)
	v_add_f32_e32 v4, v4, v5
	v_fmamk_f32 v4, v4, 0x3a800000, v221
	v_mul_f32_e32 v5, 0x4b800000, v4
	v_cmp_gt_f32_e64 s[40:41], s91, v4
	s_nop 1
	v_cndmask_b32_e64 v4, v4, v5, s[40:41]
	v_rsq_f32_e32 v4, v4
	s_nop 0
	v_mul_f32_e32 v5, 0x45800000, v4
	v_cndmask_b32_e64 v4, v4, v5, s[40:41]
	ds_write_b32 v235, v4

; #define LAS __attribute__((address_space(3)))
; __device__ __forceinline__ void hg_seq_unit(const Params& P, LAS unsigned char* lds, int layer, int g0, int nch, int h, const float* S0, float* Sout, int mode, int seg, const float* Lb, int tid, int lane, int wave) {
;     ...
;             for (int j = 0; j < seg; ++j) { float a = 0.f;
; #pragma unroll
;                 for (int c = 0; c < SEGC; ++c) a += LG[((size_t)(gb + SEGC * j + c) * 4 + h) * 128 + tid];
;                 *(LAS float*)(lds + HS_DS + (j * 128 + tid) * 4) = __expf(a); }
.LBB0_715:
	s_add_i32 s12, s58, -15
	s_ashr_i32 s13, s12, 31
	s_lshl_b64 s[12:13], s[12:13], 11
	v_lshl_add_u64 v[40:41], v[36:37], 0, s[12:13]
	global_load_dword v130, v[40:41], off
	s_add_i32 s12, s58, -14
	s_ashr_i32 s13, s12, 31
	s_lshl_b64 s[12:13], s[12:13], 11
	v_lshl_add_u64 v[40:41], v[36:37], 0, s[12:13]
	global_load_dword v131, v[40:41], off
	s_add_i32 s12, s58, -13
	s_ashr_i32 s13, s12, 31
	s_lshl_b64 s[12:13], s[12:13], 11
	v_lshl_add_u64 v[40:41], v[36:37], 0, s[12:13]
	global_load_dword v132, v[40:41], off
	s_add_i32 s12, s58, -12
	s_ashr_i32 s13, s12, 31
	s_lshl_b64 s[12:13], s[12:13], 11
	v_lshl_add_u64 v[40:41], v[36:37], 0, s[12:13]
	global_load_dword v133, v[40:41], off
	s_add_i32 s12, s58, -11
	s_ashr_i32 s13, s12, 31
	s_lshl_b64 s[12:13], s[12:13], 11
	v_lshl_add_u64 v[40:41], v[36:37], 0, s[12:13]
	global_load_dword v134, v[40:41], off
	s_add_i32 s12, s58, -10
	s_ashr_i32 s13, s12, 31
	s_lshl_b64 s[12:13], s[12:13], 11
	v_lshl_add_u64 v[40:41], v[36:37], 0, s[12:13]
	global_load_dword v135, v[40:41], off
	s_add_i32 s12, s58, -9
	s_ashr_i32 s13, s12, 31
	s_lshl_b64 s[12:13], s[12:13], 11
	v_lshl_add_u64 v[40:41], v[36:37], 0, s[12:13]
	global_load_dword v136, v[40:41], off
	s_add_i32 s12, s58, -8
	s_ashr_i32 s13, s12, 31
	s_lshl_b64 s[12:13], s[12:13], 11
	v_lshl_add_u64 v[40:41], v[36:37], 0, s[12:13]
	global_load_dword v137, v[40:41], off
	s_add_i32 s12, s58, -7
	s_ashr_i32 s13, s12, 31
	s_lshl_b64 s[12:13], s[12:13], 11
	v_lshl_add_u64 v[40:41], v[36:37], 0, s[12:13]
	global_load_dword v138, v[40:41], off
	s_add_i32 s12, s58, -6
	s_ashr_i32 s13, s12, 31
	s_lshl_b64 s[12:13], s[12:13], 11
	v_lshl_add_u64 v[40:41], v[36:37], 0, s[12:13]
	global_load_dword v139, v[40:41], off
	s_add_i32 s12, s58, -5
	s_ashr_i32 s13, s12, 31
	s_lshl_b64 s[12:13], s[12:13], 11
	v_lshl_add_u64 v[40:41], v[36:37], 0, s[12:13]
	global_load_dword v140, v[40:41], off
	s_add_i32 s12, s58, -4
	s_ashr_i32 s13, s12, 31
	s_lshl_b64 s[12:13], s[12:13], 11
	v_lshl_add_u64 v[40:41], v[36:37], 0, s[12:13]
	global_load_dword v141, v[40:41], off
	s_add_i32 s12, s58, -3
	s_ashr_i32 s13, s12, 31
	s_lshl_b64 s[12:13], s[12:13], 11
	v_lshl_add_u64 v[40:41], v[36:37], 0, s[12:13]
	global_load_dword v142, v[40:41], off
	s_add_i32 s12, s58, -2
	s_ashr_i32 s13, s12, 31
	s_lshl_b64 s[12:13], s[12:13], 11
	v_lshl_add_u64 v[40:41], v[36:37], 0, s[12:13]
	global_load_dword v143, v[40:41], off
	s_add_i32 s12, s58, -1
	s_ashr_i32 s13, s12, 31
	s_lshl_b64 s[12:13], s[12:13], 11
	v_lshl_add_u64 v[40:41], v[36:37], 0, s[12:13]
	global_load_dword v144, v[40:41], off
	s_mov_b32 s12, s58
	s_ashr_i32 s13, s12, 31
	s_lshl_b64 s[12:13], s[12:13], 11
	v_lshl_add_u64 v[40:41], v[36:37], 0, s[12:13]
	global_load_dword v145, v[40:41], off
	s_ashr_i32 s59, s58, 31
	s_add_i32 s6, s6, -1
	s_add_i32 s58, s58, 16
	s_waitcnt vmcnt(15)
	v_add_f32_e32 v39, 0, v130
	s_waitcnt vmcnt(14)
	v_add_f32_e32 v39, v39, v131
	s_waitcnt vmcnt(13)
	v_add_f32_e32 v39, v39, v132
	s_waitcnt vmcnt(12)
	v_add_f32_e32 v39, v39, v133
	s_waitcnt vmcnt(11)
	v_add_f32_e32 v39, v39, v134
	s_waitcnt vmcnt(10)
	v_add_f32_e32 v39, v39, v135
	s_waitcnt vmcnt(9)
	v_add_f32_e32 v39, v39, v136
	s_waitcnt vmcnt(8)
	v_add_f32_e32 v39, v39, v137
	s_waitcnt vmcnt(7)
	v_add_f32_e32 v39, v39, v138
	s_waitcnt vmcnt(6)
	v_add_f32_e32 v39, v39, v139
	s_waitcnt vmcnt(5)
	v_add_f32_e32 v39, v39, v140
	s_waitcnt vmcnt(4)
	v_add_f32_e32 v39, v39, v141
	s_waitcnt vmcnt(3)
	v_add_f32_e32 v39, v39, v142
	s_waitcnt vmcnt(2)
	v_add_f32_e32 v39, v39, v143
	s_waitcnt vmcnt(1)
	v_add_f32_e32 v39, v39, v144
	s_waitcnt vmcnt(0)
	v_add_f32_e32 v39, v39, v145
	v_mul_f32_e32 v39, 0x3fb8aa3b, v39
	v_exp_f32_e32 v39, v39
	ds_write_b32 v38, v39
	v_add_u32_e32 v38, 0x200, v38
	s_cmp_lg_u32 s6, 0
	s_cbranch_scc1 .LBB0_715
	v_mov_b32_e32 v36, s5
	v_mov_b64_e32 v[38:39], s[56:57]
; #define LAS __attribute__((address_space(3)))
; __device__ __forceinline__ void hg_seq_unit(const Params& P, LAS unsigned char* lds, int layer, int g0, int nch, int h, const float* S0, float* Sout, int mode, int seg, const float* Lb, int tid, int lane, int wave) {
;     ...
;             float run = 0.f;
; #pragma unroll
;             for (int c = 0; c < SEGC; ++c) { *(LAS float*)(lds + HS_DC + (c * 128 + tid) * 4) = __expf(run); run += LG[((size_t)(g0 + c) * 4 + h) * 128 + tid]; }
;             *(LAS float*)(lds + HS_DS + (seg * 128 + tid) * 4) = __expf(run);
.LBB0_717:
	v_lshl_add_u64 v[38:39], s[40:41], 0, v[38:39]
	s_ashr_i32 s51, s50, 31
	v_lshl_add_u64 v[38:39], v[2:3], 2, v[38:39]
	s_lshl_b64 s[12:13], s[50:51], 11
	v_lshl_add_u64 v[40:41], v[38:39], 0, s[12:13]
	s_mov_b32 s98, 0x1000
	s_mov_b32 s99, 0
	global_load_dword v130, v[40:41], off
	global_load_dword v131, v[40:41], off offset:2048
	v_lshl_add_u64 v[40:41], v[40:41], 0, s[98:99]
	global_load_dword v132, v[40:41], off
	global_load_dword v133, v[40:41], off offset:2048
	v_lshl_add_u64 v[40:41], v[40:41], 0, s[98:99]
	global_load_dword v134, v[40:41], off
	global_load_dword v135, v[40:41], off offset:2048
	v_lshl_add_u64 v[40:41], v[40:41], 0, s[98:99]
	global_load_dword v136, v[40:41], off
	global_load_dword v137, v[40:41], off offset:2048
	v_lshl_add_u64 v[40:41], v[40:41], 0, s[98:99]
	global_load_dword v138, v[40:41], off
	global_load_dword v139, v[40:41], off offset:2048
	v_lshl_add_u64 v[40:41], v[40:41], 0, s[98:99]
	global_load_dword v140, v[40:41], off
	global_load_dword v141, v[40:41], off offset:2048
	v_lshl_add_u64 v[40:41], v[40:41], 0, s[98:99]
	global_load_dword v142, v[40:41], off
	global_load_dword v143, v[40:41], off offset:2048
	v_lshl_add_u64 v[40:41], v[40:41], 0, s[98:99]
	global_load_dword v144, v[40:41], off
	global_load_dword v145, v[40:41], off offset:2048
	v_add_u32_e32 v37, 0, v0
	v_add_u32_e32 v37, 0x16c00, v37
	s_movk_i32 s56, 0x2000
	s_movk_i32 s57, 0x4000
	s_lshl_b32 s5, s34, 9
	s_add_i32 s5, s5, 0
	v_add_u32_e32 v0, s5, v0
	v_add_u32_e32 v0, 0x15c00, v0
	ds_write_b32 v37, v225
	s_waitcnt vmcnt(15)
	v_add_f32_e32 v3, 0, v130
	v_mul_f32_e32 v42, 0x3fb8aa3b, v3
	v_exp_f32_e32 v42, v42
	ds_write_b32 v37, v42 offset:512
	s_waitcnt vmcnt(14)
	v_add_f32_e32 v3, v3, v131
	v_mul_f32_e32 v42, 0x3fb8aa3b, v3
	v_exp_f32_e32 v42, v42
	ds_write_b32 v37, v42 offset:1024
	s_waitcnt vmcnt(13)
	v_add_f32_e32 v3, v3, v132
	v_mul_f32_e32 v42, 0x3fb8aa3b, v3
	v_exp_f32_e32 v42, v42
	ds_write_b32 v37, v42 offset:1536
	s_waitcnt vmcnt(12)
	v_add_f32_e32 v3, v3, v133
	v_mul_f32_e32 v42, 0x3fb8aa3b, v3
	v_exp_f32_e32 v42, v42
	ds_write_b32 v37, v42 offset:2048
	s_waitcnt vmcnt(11)
	v_add_f32_e32 v3, v3, v134
	v_mul_f32_e32 v42, 0x3fb8aa3b, v3
	v_exp_f32_e32 v42, v42
	ds_write_b32 v37, v42 offset:2560
	s_waitcnt vmcnt(10)
	v_add_f32_e32 v3, v3, v135
	v_mul_f32_e32 v42, 0x3fb8aa3b, v3
	v_exp_f32_e32 v42, v42
	ds_write_b32 v37, v42 offset:3072
	s_waitcnt vmcnt(9)
	v_add_f32_e32 v3, v3, v136
	v_mul_f32_e32 v42, 0x3fb8aa3b, v3
	v_exp_f32_e32 v42, v42
	ds_write_b32 v37, v42 offset:3584
	s_waitcnt vmcnt(8)
	v_add_f32_e32 v3, v3, v137
	v_mul_f32_e32 v42, 0x3fb8aa3b, v3
	v_exp_f32_e32 v42, v42
	ds_write_b32 v37, v42 offset:4096
	s_waitcnt vmcnt(7)
	v_add_f32_e32 v3, v3, v138
	v_mul_f32_e32 v42, 0x3fb8aa3b, v3
	v_exp_f32_e32 v42, v42
	ds_write_b32 v37, v42 offset:4608
	s_waitcnt vmcnt(6)
	v_add_f32_e32 v3, v3, v139
	v_mul_f32_e32 v42, 0x3fb8aa3b, v3
	v_exp_f32_e32 v42, v42
	ds_write_b32 v37, v42 offset:5120
	s_waitcnt vmcnt(5)
	v_add_f32_e32 v3, v3, v140
	v_mul_f32_e32 v42, 0x3fb8aa3b, v3
	v_exp_f32_e32 v42, v42
	ds_write_b32 v37, v42 offset:5632
	s_waitcnt vmcnt(4)
	v_add_f32_e32 v3, v3, v141
	v_mul_f32_e32 v42, 0x3fb8aa3b, v3
	v_exp_f32_e32 v42, v42
	ds_write_b32 v37, v42 offset:6144
	s_waitcnt vmcnt(3)
	v_add_f32_e32 v3, v3, v142
	v_mul_f32_e32 v42, 0x3fb8aa3b, v3
	v_exp_f32_e32 v42, v42
	ds_write_b32 v37, v42 offset:6656
	s_waitcnt vmcnt(2)
	v_add_f32_e32 v3, v3, v143
	v_mul_f32_e32 v42, 0x3fb8aa3b, v3
	v_exp_f32_e32 v42, v42
	ds_write_b32 v37, v42 offset:7168
	s_waitcnt vmcnt(1)
	v_add_f32_e32 v3, v3, v144
	v_mul_f32_e32 v42, 0x3fb8aa3b, v3
	v_exp_f32_e32 v42, v42
	ds_write_b32 v37, v42 offset:7680
	s_waitcnt vmcnt(0)
	v_add_f32_e32 v3, v3, v145
	v_mul_f32_e32 v42, 0x3fb8aa3b, v3
	v_exp_f32_e32 v42, v42
	ds_write_b32 v0, v42
